# gated-DeltaNet: each wave adds its k-step of lower(QK^T) c' to its own Q S partial (one MFMA instead of four on one wave); outputs finished one chunk later
# baseline (speedup 1.0000x reference)
; __device__ __forceinline__ int otid() { int t = threadIdx.x; asm volatile("" : "+v"(t)); return t; }
; __device__ __forceinline__ void gdn_item(const Params& p, int item, float* sm) {
;   const int b = item >> 5, h = (item >> 3) & 3, c0 = (item & 7) * 16;
;   const bf16_t* gp = (const bf16_t*)p.out;
;   const float* gg = (const float*)(p.ws + OFF_GG);
;   bf16_t* O = (bf16_t*)(p.ws + OFF_O);
;   constexpr int TC = 16;
;   constexpr int BUF = 2 * TC * 128 + TC * 16 + 2 * TC + TC * 16 + TC;
;   const int tid = otid(), lane = tid & 63, wave = tid >> 6;
;   const int sub = lane & 15, cw = wave * 4 + (lane >> 4);
;   const int ltt = tid >> 4, lseg = tid & 15;
;   float S[8];
; #pragma unroll
;   for (int i = 0; i < 8; i++) S[i] = 0.f;
;   const size_t rowb = (size_t)b * LP;
;   uint4 pq, pk; bf16_t pv; float pg = 0.f, pb = 0.f;
;     ...
;   __syncthreads();
;   GDN_LOAD(PADR)
;   GDN_STORE(0)
;   __syncthreads();
.Lgd_item:
	s_setprio 3
	v_readlane_b32 s14, v244, 27
	v_readlane_b32 s8, v247, 3
	v_readlane_b32 s9, v247, 4
	v_readlane_b32 s4, v247, 1
	v_readlane_b32 s5, v247, 2
	v_and_b32_e32 v136, 15, v2
	v_lshrrev_b32_e32 v137, 4, v2
	v_bfe_u32 v138, v2, 4, 2
	v_lshrrev_b32_e32 v139, 6, v2
	s_lshr_b32 s10, s14, 5
	s_bfe_u32 s11, s14, 0x20003
	s_and_b32 s12, s14, 7
	s_lshl_b32 s12, s12, 5
	s_mul_i32 s13, s10, 0x2080
	s_add_i32 s13, s13, 0x70
	s_add_u32 s6, s8, 0x19c8c000
	s_addc_u32 s7, s9, 0
	s_add_u32 s8, s8, 0x19d90000
	s_addc_u32 s9, s9, 0
	s_lshl_b32 s14, s10, 2
	s_add_i32 s14, s14, s11
	s_mul_i32 s14, s14, 0x80400
	s_add_u32 s10, s4, 0x71a0000
	s_addc_u32 s15, s5, 0
	s_add_u32 s10, s10, s14
	s_addc_u32 s11, s15, 0
	v_readfirstlane_b32 s100, v139
	v_lshlrev_b32_e32 v151, 9, v136
	v_lshl_add_u32 v151, v139, 7, v151
	v_lshl_add_u32 v151, v138, 4, v151
	v_lshlrev_b32_e32 v152, 11, v138
	v_lshl_add_u32 v152, v139, 7, v152
	v_lshl_add_u32 v152, v136, 2, v152
	v_lshlrev_b32_e32 v153, 6, v136
	v_lshl_add_u32 v153, v138, 4, v153
	v_lshlrev_b32_e32 v154, 4, v138
	v_and_b32_e32 v140, 63, v2
	v_lshlrev_b32_e32 v156, 4, v140
	v_add_u32_e32 v156, 0x8a00, v156
	s_mul_i32 s101, s100, 0xc00
	v_add_u32_e32 v155, s101, v156
	v_lshlrev_b32_e32 v157, 5, v2
	v_lshl_add_u32 v158, v136, 4, v137
	v_lshlrev_b32_e32 v158, 2, v158
	v_add_u32_e32 v158, 16384, v158
	v_lshlrev_b32_e32 v159, 2, v136
	v_lshlrev_b32_e32 v141, 2, v138
	v_add_u32_e32 v142, 0, v141
	v_cmp_le_u32_e32 vcc, v142, v136
	s_nop 1
	v_cndmask_b32_e64 v166, 0, 1.0, vcc
	v_add_u32_e32 v142, 1, v141
	v_cmp_le_u32_e32 vcc, v142, v136
	s_nop 1
	v_cndmask_b32_e64 v167, 0, 1.0, vcc
	v_add_u32_e32 v142, 2, v141
	v_cmp_le_u32_e32 vcc, v142, v136
	s_nop 1
	v_cndmask_b32_e64 v168, 0, 1.0, vcc
	v_add_u32_e32 v142, 3, v141
	v_cmp_le_u32_e32 vcc, v142, v136
	s_nop 1
	v_cndmask_b32_e64 v169, 0, 1.0, vcc
	v_readlane_b32 s101, v244, 27
	s_bfe_u32 s101, s101, 0x20003
	v_add_u32_e32 v142, s13, v137
	s_lshl_b32 s14, s101, 8
	v_lshl_add_u32 v143, v136, 4, s14
	s_movk_i32 s15, 0xc00
	v_mad_u32_u24 v118, v142, s15, v143
	s_add_i32 s14, s14, s12
	v_lshl_add_u32 v143, v136, 1, s14
	v_mad_u32_u24 v119, v142, s15, v143
	v_add_u32_e32 v119, 0x800, v119
	v_add_u32_e32 v142, s13, v136
	s_lshl_b32 s15, s101, 2
	v_lshl_add_u32 v140, v142, 5, s15
	v_add_u32_e32 v142, s13, v141
	v_lshl_add_u32 v57, v142, 11, v143
	v_add_u32_e32 v57, 0x400, v57
	v_add_u32_e32 v58, 0x1000, v57
	v_lshlrev_b32_e32 v59, 6, v136
	v_lshl_add_u32 v59, v138, 4, v59
	v_cmp_eq_u32_e32 vcc, 0, v139
	s_nop 1
	v_cndmask_b32_e64 v170, 0, 1.0, vcc
	v_cmp_eq_u32_e32 vcc, 1, v139
	s_nop 1
	v_cndmask_b32_e64 v171, 0, 1.0, vcc
	v_cmp_eq_u32_e32 vcc, 2, v139
	s_nop 1
	v_cndmask_b32_e64 v172, 0, 1.0, vcc
	v_cmp_eq_u32_e32 vcc, 3, v139
	s_nop 1
	v_cndmask_b32_e64 v173, 0, 1.0, vcc
	v_lshl_add_u32 v179, v139, 2, v59
	v_mov_b32_e32 v174, 0
	v_mov_b32_e32 v175, 0
	v_mov_b32_e32 v176, 0
	v_mov_b32_e32 v177, 0
	s_sub_u32 s8, s8, 0x8000
	s_subb_u32 s9, s9, 0
	v_readlane_b32 s14, v244, 27
	s_lshr_b32 s14, s14, 3
	s_mul_i32 s12, s14, 0x80400
	v_readlane_b32 s14, v247, 3
	v_readlane_b32 s15, v247, 4
	s_add_u32 s14, s14, 0xac40000
	s_addc_u32 s15, s15, 0
	s_add_u32 s14, s14, s12
	s_addc_u32 s15, s15, 0
	v_mov_b32_e32 v12, 0
	v_mov_b32_e32 v13, 0
	v_mov_b32_e32 v14, 0
	v_mov_b32_e32 v15, 0
	v_mov_b32_e32 v16, 0
	v_mov_b32_e32 v17, 0
	v_mov_b32_e32 v18, 0
	v_mov_b32_e32 v19, 0
	s_barrier
	global_load_dwordx4 v[108:111], v118, s[4:5]
	global_load_dwordx4 v[112:115], v118, s[4:5] offset:1024
	global_load_ushort v116, v119, s[4:5]
	global_load_dword v117, v140, s[6:7]
	s_add_u32 s4, s4, 0xc000
	s_addc_u32 s5, s5, 0
	s_add_u32 s6, s6, 0x200
	s_addc_u32 s7, s7, 0
	global_load_dwordx4 v[88:91], v59, s[10:11]
	s_add_u32 s10, s10, 0x400
	s_addc_u32 s11, s11, 0
	global_load_dword v92, v179, s[14:15]
	s_add_u32 s14, s14, 0x400
	s_addc_u32 s15, s15, 0
	v_mov_b32_e32 v148, v157
	v_mov_b32_e32 v149, v158
	v_mov_b32_e32 v150, v159
	s_waitcnt vmcnt(0)
	v_lshlrev_b32_e32 v120, 16, v108
	v_and_b32_e32 v121, 0xffff0000, v108
	v_lshlrev_b32_e32 v122, 16, v109
	v_and_b32_e32 v123, 0xffff0000, v109
	v_lshlrev_b32_e32 v124, 16, v110
	v_and_b32_e32 v125, 0xffff0000, v110
	v_lshlrev_b32_e32 v126, 16, v111
	v_and_b32_e32 v127, 0xffff0000, v111
	v_lshlrev_b32_e32 v128, 16, v112
	v_and_b32_e32 v129, 0xffff0000, v112
	v_lshlrev_b32_e32 v130, 16, v113
	v_and_b32_e32 v131, 0xffff0000, v113
	v_lshlrev_b32_e32 v132, 16, v114
	v_and_b32_e32 v133, 0xffff0000, v114
	v_lshlrev_b32_e32 v134, 16, v115
	v_and_b32_e32 v135, 0xffff0000, v115
	v_mov_b32_e32 v136, v117
	v_lshlrev_b32_e32 v137, 16, v116
	s_nop 0
	v_add_f32_dpp v136, v136, v136 row_shr:1 row_mask:0xf bank_mask:0xf bound_ctrl:1
	s_nop 1
	v_add_f32_dpp v136, v136, v136 row_shr:2 row_mask:0xf bank_mask:0xf bound_ctrl:1
	s_nop 1
	v_add_f32_dpp v136, v136, v136 row_shr:4 row_mask:0xf bank_mask:0xf bound_ctrl:1
	s_nop 1
	v_add_f32_dpp v136, v136, v136 row_shr:8 row_mask:0xf bank_mask:0xf bound_ctrl:1
	s_nop 0
	v_max_f32_e32 v136, 0xc2a00000, v136
	v_mul_f32_e32 v136, 0x3fb8aa3b, v136
	v_exp_f32_e32 v138, v136
	v_exp_f32_e64 v139, -v136
	s_nop 0
	v_mul_f32_e32 v136, 0x3db504f3, v138
	ds_write_b128 v148, v[120:123]
	ds_write_b128 v148, v[124:127] offset:16
	ds_write_b128 v148, v[128:131] offset:8192
	ds_write_b128 v148, v[132:135] offset:8208
	ds_write_b32 v149, v137
	ds_write_b32 v150, v139 offset:17408
	ds_write_b32 v150, v138 offset:17536
	ds_write_b32 v150, v136 offset:17472
	global_load_dwordx4 v[108:111], v118, s[4:5]
	global_load_dwordx4 v[112:115], v118, s[4:5] offset:1024
	global_load_ushort v116, v119, s[4:5]
	global_load_dword v117, v140, s[6:7]
	s_add_u32 s4, s4, 0xc000
	s_addc_u32 s5, s5, 0
	s_add_u32 s6, s6, 0x200
	s_addc_u32 s7, s7, 0
	s_mov_b32 s0, 0
	s_mov_b32 s1, 0
	s_waitcnt lgkmcnt(0)
	s_barrier
; __device__ __forceinline__ void gdn_item(const Params& p, int item, float* sm) {
;     ...
;   for (int ch = 0; ch < NCH; ch++) {
;     const int bi = ch & 1;
;     const int t0 = PADR + ch * TC;
;     if (ch + 1 < NCH) GDN_LOAD(t0 + TC)
;     {
;       const float* bq = sm + bi * BUF;
;       const float* bk = bq + TC * 128;
;       const float* bv = bq + 2 * TC * 128;
;       const float* bg = bv + TC * 16;
;       float* bo = sm + bi * BUF + 2 * TC * 128 + TC * 16 + 2 * TC;
;       float oreg[TC];
; #pragma unroll
;       for (int t = 0; t < TC; t++) {
;         const float4 k0 = *(const float4*)(bk + t * 128 + sub * 4);
;         const float4 k1 = *(const float4*)(bk + t * 128 + 64 + sub * 4);
;         const float4 q0 = *(const float4*)(bq + t * 128 + sub * 4);
;         const float4 q1 = *(const float4*)(bq + t * 128 + 64 + sub * 4);
;         const float v = bv[t * 16 + cw];
;         const float g = bg[t], be = bg[TC + t];
;         const float qk = bo[TC * 16 + t];
;         float pa = k0.x * S[0] + k0.y * S[1];
;         float pb2 = k0.z * S[2] + k0.w * S[3];
;         float qa = q0.x * S[0] + q0.y * S[1];
;         float qb2 = q0.z * S[2] + q0.w * S[3];
;         pa += k1.x * S[4] + k1.y * S[5];
;         pb2 += k1.z * S[6] + k1.w * S[7];
;         qa += q1.x * S[4] + q1.y * S[5];
;         qb2 += q1.z * S[6] + q1.w * S[7];
;         const float ks = dpp_sum16(pa + pb2);
;         const float qs = dpp_sum16(qa + qb2);
;         const float coef = be * (v - g * ks);
;         const float oo = g * qs + coef * qk;
;         S[0] = g * S[0] + coef * k0.x; S[1] = g * S[1] + coef * k0.y; S[2] = g * S[2] + coef * k0.z; S[3] = g * S[3] + coef * k0.w;
;         S[4] = g * S[4] + coef * k1.x; S[5] = g * S[5] + coef * k1.y; S[6] = g * S[6] + coef * k1.z; S[7] = g * S[7] + coef * k1.w;
;         oreg[t] = oo * 0.08838834764831845f;
;       }
;       if (sub == 0) {
; #pragma unroll
;         for (int t = 0; t < TC; t++) bo[t * 16 + cw] = oreg[t];
;       }
;     }
;     if (ch + 1 < NCH) GDN_STORE(bi ^ 1)
;     __syncthreads();
;     {
;       const float ov = sm[bi * BUF + 2 * TC * 128 + TC * 16 + 2 * TC + ltt * 16 + lseg];
;       O[(rowb + t0 + ltt) * D + 512 + h * 128 + c0 + lseg] = f2bf(ov);
;     }
.Lgd_chunk:
	v_add_u32_e32 v141, s1, v151
	v_add_u32_e32 v142, s1, v152
	v_add_u32_e32 v143, s1, v153
	v_add_u32_e32 v144, s1, v154
	v_mov_b32_e32 v145, s1
	s_xor_b32 s2, s1, 0x4500
	s_and_b32 s12, s0, 1
	s_mul_i32 s12, s12, 0x3000
	v_add_u32_e32 v146, s12, v155
	v_add_u32_e32 v147, s12, v156
	s_xor_b32 s101, s12, 0x3000
	v_add_u32_e32 v178, s101, v156
	ds_read_b128 v[20:23], v141 offset:8192
	ds_read_b128 v[28:31], v141 offset:0
	ds_read_b128 v[24:27], v141 offset:8256
	ds_read_b128 v[32:35], v141 offset:64
	v_add_u32_e32 v148, s2, v157
	v_add_u32_e32 v149, s2, v158
	v_add_u32_e32 v150, s2, v159
	s_waitcnt lgkmcnt(0)
	v_mfma_f32_16x16x4_f32 v[60:63], v20, v12, 0
	ds_read_b32 v36, v142 offset:8192
	v_mfma_f32_16x16x4_f32 v[64:67], v28, v12, 0
	ds_read_b32 v37, v142 offset:8704
	v_mfma_f32_16x16x4_f32 v[60:63], v21, v13, v[60:63]
	ds_read_b32 v38, v142 offset:9216
	v_mfma_f32_16x16x4_f32 v[64:67], v29, v13, v[64:67]
	ds_read_b32 v39, v142 offset:9728
	s_waitcnt vmcnt(0)
	v_lshlrev_b32_e32 v120, 16, v108
	v_and_b32_e32 v121, 0xffff0000, v108
	v_lshlrev_b32_e32 v122, 16, v109
	v_mfma_f32_16x16x4_f32 v[60:63], v22, v14, v[60:63]
	ds_read_b32 v40, v142 offset:8256
	v_and_b32_e32 v123, 0xffff0000, v109
	v_lshlrev_b32_e32 v124, 16, v110
	v_and_b32_e32 v125, 0xffff0000, v110
	v_mfma_f32_16x16x4_f32 v[64:67], v30, v14, v[64:67]
	ds_read_b32 v41, v142 offset:8768
	v_lshlrev_b32_e32 v126, 16, v111
	v_and_b32_e32 v127, 0xffff0000, v111
	v_lshlrev_b32_e32 v128, 16, v112
	v_and_b32_e32 v129, 0xffff0000, v112
	v_mfma_f32_16x16x4_f32 v[60:63], v23, v15, v[60:63]
	ds_read_b32 v42, v142 offset:9280
	v_lshlrev_b32_e32 v130, 16, v113
	v_and_b32_e32 v131, 0xffff0000, v113
	v_lshlrev_b32_e32 v132, 16, v114
	v_mfma_f32_16x16x4_f32 v[64:67], v31, v15, v[64:67]
	ds_read_b32 v43, v142 offset:9792
	v_and_b32_e32 v133, 0xffff0000, v114
	v_lshlrev_b32_e32 v134, 16, v115
	v_and_b32_e32 v135, 0xffff0000, v115
	v_mov_b32_e32 v136, v117
	v_mfma_f32_16x16x4_f32 v[60:63], v24, v16, v[60:63]
	ds_read_b128 v[44:47], v143 offset:16384
	v_lshlrev_b32_e32 v137, 16, v116
	s_nop 0
	v_add_f32_dpp v136, v136, v136 row_shr:1 row_mask:0xf bank_mask:0xf bound_ctrl:1
	v_mfma_f32_16x16x4_f32 v[64:67], v32, v16, v[64:67]
	ds_read_b128 v[48:51], v144 offset:17408
	s_nop 1
	v_add_f32_dpp v136, v136, v136 row_shr:2 row_mask:0xf bank_mask:0xf bound_ctrl:1
	s_nop 1
	v_add_f32_dpp v136, v136, v136 row_shr:4 row_mask:0xf bank_mask:0xf bound_ctrl:1
	v_mfma_f32_16x16x4_f32 v[60:63], v25, v17, v[60:63]
	ds_read_b128 v[52:55], v144 offset:17472
	s_nop 1
	v_add_f32_dpp v136, v136, v136 row_shr:8 row_mask:0xf bank_mask:0xf bound_ctrl:1
	s_nop 0
	v_mfma_f32_16x16x4_f32 v[64:67], v33, v17, v[64:67]
	ds_read_b32 v56, v145 offset:17596
	v_max_f32_e32 v136, 0xc2a00000, v136
	v_mul_f32_e32 v136, 0x3fb8aa3b, v136
	v_exp_f32_e32 v138, v136
	v_exp_f32_e64 v139, -v136
	v_mfma_f32_16x16x4_f32 v[60:63], v26, v18, v[60:63]
	s_nop 0
	v_mul_f32_e32 v136, 0x3db504f3, v138
	ds_write_b128 v148, v[120:123]
	v_mfma_f32_16x16x4_f32 v[64:67], v34, v18, v[64:67]
	ds_write_b128 v148, v[124:127] offset:16
	ds_write_b128 v148, v[128:131] offset:8192
	ds_write_b128 v148, v[132:135] offset:8208
	ds_write_b32 v149, v137
	v_mfma_f32_16x16x4_f32 v[60:63], v27, v19, v[60:63]
	ds_write_b32 v150, v139 offset:17408
	ds_write_b32 v150, v138 offset:17536
	ds_write_b32 v150, v136 offset:17472
	v_mfma_f32_16x16x4_f32 v[64:67], v35, v19, v[64:67]
	global_load_dwordx4 v[108:111], v118, s[4:5]
	global_load_dwordx4 v[112:115], v118, s[4:5] offset:1024
	global_load_ushort v116, v119, s[4:5]
	global_load_dword v117, v140, s[6:7]
	s_cmp_lt_u32 s0, 0x1fe
	s_cselect_b32 s12, 0xc000, 0
	s_cselect_b32 s101, 0x200, 0
	s_add_u32 s4, s4, s12
	s_addc_u32 s5, s5, 0
	s_add_u32 s6, s6, s101
	s_addc_u32 s7, s7, 0
	s_nop 3
	ds_write_b128 v146, v[60:63]
	s_waitcnt lgkmcnt(0)
	s_barrier
	ds_read_b128 v[72:75], v147 offset:0
	ds_read_b128 v[76:79], v147 offset:3072
	ds_read_b128 v[80:83], v147 offset:6144
	ds_read_b128 v[84:87], v147 offset:9216
	s_waitcnt lgkmcnt(0)
	v_add_f32_e32 v72, v72, v76
	v_add_f32_e32 v80, v80, v84
	v_add_f32_e32 v73, v73, v77
	v_add_f32_e32 v81, v81, v85
	v_add_f32_e32 v74, v74, v78
	v_add_f32_e32 v82, v82, v86
	v_add_f32_e32 v75, v75, v79
	v_add_f32_e32 v83, v83, v87
	v_add_f32_e32 v72, v72, v80
	v_add_f32_e32 v73, v73, v81
	v_add_f32_e32 v74, v74, v82
	v_add_f32_e32 v75, v75, v83
	v_fma_f32 v96, v44, v48, -v72
	v_fma_f32 v97, v45, v49, -v73
	v_fma_f32 v98, v46, v50, -v74
	v_fma_f32 v99, v47, v51, -v75
	s_nop 1
	v_mfma_f32_16x16x4_f32 v[100:103], v88, v96, 0
	v_mfma_f32_16x16x4_f32 v[100:103], v89, v97, v[100:103]
	v_mfma_f32_16x16x4_f32 v[100:103], v90, v98, v[100:103]
	v_mfma_f32_16x16x4_f32 v[100:103], v91, v99, v[100:103]
	global_load_dwordx4 v[88:91], v59, s[10:11]
	s_cmp_lt_u32 s0, 0x1ff
	s_cselect_b32 s12, 0x400, 0
	s_add_u32 s10, s10, s12
	s_addc_u32 s11, s11, 0
	s_cmp_eq_u32 s0, 0
	s_cbranch_scc1 .Lgd_noout
	s_add_i32 s12, s0, -1
	s_and_b32 s12, s12, 3
	s_cmp_eq_u32 s12, s100
	s_cbranch_scc0 .Lgd_noout
	ds_read_b128 v[72:75], v178 offset:1024
	ds_read_b128 v[76:79], v178 offset:4096
	ds_read_b128 v[80:83], v178 offset:7168
	ds_read_b128 v[84:87], v178 offset:10240
	s_waitcnt lgkmcnt(0)
	v_add_f32_e32 v72, v72, v76
	v_add_f32_e32 v80, v80, v84
	v_add_f32_e32 v73, v73, v77
	v_add_f32_e32 v81, v81, v85
	v_add_f32_e32 v74, v74, v78
	v_add_f32_e32 v82, v82, v86
	v_add_f32_e32 v75, v75, v79
	v_add_f32_e32 v83, v83, v87
	v_add_f32_e32 v104, v72, v80
	v_add_f32_e32 v105, v73, v81
	v_add_f32_e32 v106, v74, v82
	v_add_f32_e32 v107, v75, v83
	v_mul_f32_e32 v104, v104, v174
	v_mul_f32_e32 v105, v105, v175
	v_mul_f32_e32 v106, v106, v176
	v_mul_f32_e32 v107, v107, v177
	v_cvt_pk_bf16_f32 v104, v104, v104
	v_cvt_pk_bf16_f32 v105, v105, v105
	v_cvt_pk_bf16_f32 v106, v106, v106
	v_cvt_pk_bf16_f32 v107, v107, v107
	global_store_short v57, v104, s[8:9]
	global_store_short v57, v105, s[8:9] offset:2048
	global_store_short v58, v106, s[8:9]
	global_store_short v58, v107, s[8:9] offset:2048
	s_branch .Lgd_outd
; __device__ __forceinline__ void gdn_item(const Params& p, int item, float* sm) {
;     ...
;         const float ks = dpp_sum16(pa + pb2);
;         const float qs = dpp_sum16(qa + qb2);
;         const float coef = be * (v - g * ks);
;         const float oo = g * qs + coef * qk;
;         S[0] = g * S[0] + coef * k0.x; S[1] = g * S[1] + coef * k0.y; S[2] = g * S[2] + coef * k0.z; S[3] = g * S[3] + coef * k0.w;
;         S[4] = g * S[4] + coef * k1.x; S[5] = g * S[5] + coef * k1.y; S[6] = g * S[6] + coef * k1.z; S[7] = g * S[7] + coef * k1.w;
;         oreg[t] = oo * 0.08838834764831845f;
;       }
;       if (sub == 0) {
; #pragma unroll
;         for (int t = 0; t < TC; t++) bo[t * 16 + cw] = oreg[t];
;       }
;     }
;     if (ch + 1 < NCH) GDN_STORE(bi ^ 1)
;     __syncthreads();
;     {
;       const float ov = sm[bi * BUF + 2 * TC * 128 + TC * 16 + 2 * TC + ltt * 16 + lseg];
;       O[(rowb + t0 + ltt) * D + 512 + h * 128 + c0 + lseg] = f2bf(ov);
;     }
;   }
;     ...
;   __syncthreads();
.Lgd_noout:
	s_nop 7
	s_nop 3
.Lgd_outd:
	v_mul_f32_e32 v93, v100, v170
	v_fmac_f32_e32 v93, v101, v171
	v_fmac_f32_e32 v93, v102, v172
	v_fmac_f32_e32 v93, v103, v173
	s_nop 1
	v_mfma_f32_16x16x4_f32 v[64:67], v92, v93, v[64:67]
	global_load_dword v92, v179, s[14:15]
	s_cmp_lt_u32 s0, 0x1ff
	s_cselect_b32 s101, 0x400, 0
	s_add_u32 s14, s14, s101
	s_addc_u32 s15, s15, 0
	v_mfma_f32_16x16x4_f32 v[12:15], v36, v100, v[12:15]
	v_mfma_f32_16x16x4_f32 v[16:19], v40, v100, v[16:19]
	v_mfma_f32_16x16x4_f32 v[12:15], v37, v101, v[12:15]
	v_mfma_f32_16x16x4_f32 v[16:19], v41, v101, v[16:19]
	v_mfma_f32_16x16x4_f32 v[12:15], v38, v102, v[12:15]
	v_mfma_f32_16x16x4_f32 v[16:19], v42, v102, v[16:19]
	v_mfma_f32_16x16x4_f32 v[12:15], v39, v103, v[12:15]
	v_mfma_f32_16x16x4_f32 v[16:19], v43, v103, v[16:19]
	s_add_u32 s8, s8, 0x8000
	s_addc_u32 s9, s9, 0
	v_mov_b32_e32 v174, v52
	v_mov_b32_e32 v175, v53
	v_mov_b32_e32 v176, v54
	v_mov_b32_e32 v177, v55
	ds_write_b128 v146, v[64:67] offset:1024
	s_nop 4
	v_mul_f32_e32 v12, v12, v56
	v_mul_f32_e32 v13, v13, v56
	v_mul_f32_e32 v14, v14, v56
	v_mul_f32_e32 v15, v15, v56
	v_mul_f32_e32 v16, v16, v56
	v_mul_f32_e32 v17, v17, v56
	v_mul_f32_e32 v18, v18, v56
	v_mul_f32_e32 v19, v19, v56
	s_mov_b32 s1, s2
	s_add_i32 s0, s0, 1
	s_cmp_lg_u32 s0, 513
	s_cbranch_scc1 .Lgd_chunk
	s_waitcnt vmcnt(0) lgkmcnt(0)
	s_barrier
	s_cmp_eq_u32 s100, 0
	s_cbranch_scc0 .Lgd_fin
	v_mov_b32_e32 v178, v156
	ds_read_b128 v[72:75], v178 offset:1024
	ds_read_b128 v[76:79], v178 offset:4096
	ds_read_b128 v[80:83], v178 offset:7168
	ds_read_b128 v[84:87], v178 offset:10240
	s_waitcnt lgkmcnt(0)
	v_add_f32_e32 v72, v72, v76
	v_add_f32_e32 v80, v80, v84
	v_add_f32_e32 v73, v73, v77
	v_add_f32_e32 v81, v81, v85
	v_add_f32_e32 v74, v74, v78
	v_add_f32_e32 v82, v82, v86
	v_add_f32_e32 v75, v75, v79
	v_add_f32_e32 v83, v83, v87
	v_add_f32_e32 v104, v72, v80
	v_add_f32_e32 v105, v73, v81
	v_add_f32_e32 v106, v74, v82
	v_add_f32_e32 v107, v75, v83
	v_mul_f32_e32 v104, v104, v174
	v_mul_f32_e32 v105, v105, v175
	v_mul_f32_e32 v106, v106, v176
	v_mul_f32_e32 v107, v107, v177
	v_cvt_pk_bf16_f32 v104, v104, v104
	v_cvt_pk_bf16_f32 v105, v105, v105
	v_cvt_pk_bf16_f32 v106, v106, v106
	v_cvt_pk_bf16_f32 v107, v107, v107
	global_store_short v57, v104, s[8:9]
	global_store_short v57, v105, s[8:9] offset:2048
	global_store_short v58, v106, s[8:9]
	global_store_short v58, v107, s[8:9] offset:2048
.Lgd_fin:
	s_waitcnt vmcnt(0) lgkmcnt(0)
	s_setprio 0
